# w_in GEMM phase offset raised to about 10us (5 sleeps) for blockIdx bit-3 workgroups
# baseline (speedup 1.0000x reference)
.LBB0_232:
	s_or_b64 exec, exec, s[0:1]
	v_mov_b32_e32 v8, v254
	s_bitcmp0_b32 s2, 3
	s_cbranch_scc1 .Lstg2_go
	s_sleep 64
	s_sleep 64
	s_sleep 64
	s_sleep 64
	s_sleep 64
